# scan producer: next chunk rows loaded straight into the loop-carried registers via scalar row bases (no 64-bit VALU address math, no register copies, bf16 a via d16_hi loads)
# speedup vs baseline: 1.0069x; 1.0069x over previous
.LBB0_1240:
	s_cmp_gt_u32 s87, 61
	s_cbranch_scc1 .LBB0_1236
	v_readfirstlane_b32 s90, v20
	v_readfirstlane_b32 s91, v21
	s_add_i32 s89, s39, s88
	s_add_i32 s89, s89, 32
	v_lshlrev_b32_e32 v76, 2, v136
	v_lshlrev_b32_e32 v78, 1, v136
	s_mul_i32 s92, s89, 0x3480
	v_add_u32_e32 v77, 0x2000, v76
	s_add_u32 s90, s90, s92
	s_addc_u32 s91, s91, 0
	s_add_u32 s90, s90, 0x1000
	s_addc_u32 s91, s91, 0
	s_and_b32 s92, s89, 0x7f8
	s_cmp_lg_u32 s92, 0
	s_cselect_b32 s92, 0x3480, 0
	s_sub_u32 s92, s90, s92
	s_subb_u32 s93, s91, 0
	global_load_dword v72, v76, s[92:93] offset:-4096
	global_load_dword v73, v76, s[92:93]
	global_load_dword v74, v77, s[92:93] offset:-4096
	v_readfirstlane_b32 s92, v22
	v_readfirstlane_b32 s93, v23
	global_load_dword v40, v76, s[90:91] offset:-4096
	global_load_dword v41, v76, s[90:91]
	global_load_dword v42, v77, s[90:91] offset:-4096
	s_add_u32 s90, s90, 0x3480
	s_addc_u32 s91, s91, 0
	global_load_dword v44, v76, s[90:91] offset:-4096
	global_load_dword v45, v76, s[90:91]
	global_load_dword v46, v77, s[90:91] offset:-4096
	s_add_u32 s90, s90, 0x3480
	s_addc_u32 s91, s91, 0
	global_load_dword v48, v76, s[90:91] offset:-4096
	global_load_dword v49, v76, s[90:91]
	global_load_dword v50, v77, s[90:91] offset:-4096
	s_add_u32 s90, s90, 0x3480
	s_addc_u32 s91, s91, 0
	global_load_dword v52, v76, s[90:91] offset:-4096
	global_load_dword v53, v76, s[90:91]
	global_load_dword v54, v77, s[90:91] offset:-4096
	s_add_u32 s90, s90, 0x3480
	s_addc_u32 s91, s91, 0
	global_load_dword v56, v76, s[90:91] offset:-4096
	global_load_dword v57, v76, s[90:91]
	global_load_dword v58, v77, s[90:91] offset:-4096
	s_add_u32 s90, s90, 0x3480
	s_addc_u32 s91, s91, 0
	global_load_dword v60, v76, s[90:91] offset:-4096
	global_load_dword v61, v76, s[90:91]
	global_load_dword v62, v77, s[90:91] offset:-4096
	s_add_u32 s90, s90, 0x3480
	s_addc_u32 s91, s91, 0
	global_load_dword v64, v76, s[90:91] offset:-4096
	global_load_dword v65, v76, s[90:91]
	global_load_dword v66, v77, s[90:91] offset:-4096
	s_add_u32 s90, s90, 0x3480
	s_addc_u32 s91, s91, 0
	global_load_dword v68, v76, s[90:91] offset:-4096
	global_load_dword v69, v76, s[90:91]
	global_load_dword v70, v77, s[90:91] offset:-4096
	s_lshl_b32 s44, s89, 12
	s_add_u32 s92, s92, s44
	s_addc_u32 s93, s93, 0
	s_add_u32 s92, s92, 0x1000
	s_addc_u32 s93, s93, 0
	v_readfirstlane_b32 s90, v24
	v_readfirstlane_b32 s91, v25
	global_load_dword v43, v76, s[92:93] offset:-4096
	global_load_dword v47, v76, s[92:93]
	s_add_u32 s92, s92, 0x2000
	s_addc_u32 s93, s93, 0
	global_load_dword v51, v76, s[92:93] offset:-4096
	global_load_dword v55, v76, s[92:93]
	s_add_u32 s92, s92, 0x2000
	s_addc_u32 s93, s93, 0
	global_load_dword v59, v76, s[92:93] offset:-4096
	global_load_dword v63, v76, s[92:93]
	s_add_u32 s92, s92, 0x2000
	s_addc_u32 s93, s93, 0
	global_load_dword v67, v76, s[92:93] offset:-4096
	global_load_dword v71, v76, s[92:93]
	s_add_u32 s90, s90, s44
	s_addc_u32 s91, s91, 0
	s_add_u32 s90, s90, 0x1000
	s_addc_u32 s91, s91, 0
	global_load_short_d16_hi v13, v78, s[90:91] offset:-4096
	global_load_short_d16_hi v12, v78, s[90:91]
	s_add_u32 s90, s90, 0x2000
	s_addc_u32 s91, s91, 0
	global_load_short_d16_hi v15, v78, s[90:91] offset:-4096
	global_load_short_d16_hi v14, v78, s[90:91]
	s_add_u32 s90, s90, 0x2000
	s_addc_u32 s91, s91, 0
	global_load_short_d16_hi v17, v78, s[90:91] offset:-4096
	global_load_short_d16_hi v16, v78, s[90:91]
	s_add_u32 s90, s90, 0x2000
	s_addc_u32 s91, s91, 0
	global_load_short_d16_hi v19, v78, s[90:91] offset:-4096
	global_load_short_d16_hi v18, v78, s[90:91]
	s_branch .LBB0_1236
.LBB0_1243:
	s_branch .LBB0_1235
.LBB0_1245:
	s_and_b64 vcc, exec, s[36:37]
	s_cbranch_vccz .LBB0_1231
	s_ashr_i32 s39, s38, 31
	s_lshl_b64 s[38:39], s[38:39], 14
	s_add_u32 s38, s3, s38
	s_addc_u32 s39, s46, s39
	v_lshlrev_b32_e32 v8, 8, v75
	v_lshl_add_u64 v[4:5], s[38:39], 0, v[8:9]
	v_mov_b32_e32 v11, v9
	v_lshl_add_u64 v[4:5], v[4:5], 0, v[10:11]
	global_store_dwordx4 v[4:5], v[0:3], off
	s_branch .LBB0_1231
